# x-conversion loop stores as global_store (no lgkmcnt coupling) on top of dppsum
# baseline (speedup 1.0000x reference)
; __device__ __forceinline__ unsigned cvt_pk_bf16(float lo, float hi) { const f32x2cv v = {lo, hi}; const bf16x2cv b = __builtin_convertvector(v, bf16x2cv); return __builtin_bit_cast(unsigned, b); }
; __device__ __forceinline__ float wave_sum(float v) {
; #pragma unroll
;     for (int o = 1; o < 64; o <<= 1) v += __shfl_xor(v, o);
;     return v;
; }
; __device__ __forceinline__ void row_to_bf16(const float* xrow, bf16* orow, float* ssqrow, bool normalise, int lane) {
;     const f32x4* xr = (const f32x4*)xrow + lane; f32x4 v[4]; float s = 0.f;
; #pragma unroll
;     for (int j = 0; j < 4; ++j) { v[j] = xr[64 * j]; s += (v[j][0] * v[j][0] + v[j][1] * v[j][1]) + (v[j][2] * v[j][2] + v[j][3] * v[j][3]); }
;     s = wave_sum(s);
;     const float rs = normalise ? 1.0f / sqrtf(s * (1.f / DM) + EPS) : 1.f;
;     v2u* o8 = (v2u*)orow + lane;
; #pragma unroll
;     for (int j = 0; j < 4; ++j) { v2u w; w.x = cvt_pk_bf16(v[j][0] * rs, v[j][1] * rs); w.y = cvt_pk_bf16(v[j][2] * rs, v[j][3] * rs); o8[64 * j] = w; }
;     if (ssqrow && lane < 16) ssqrow[lane] = (lane == 0) ? s : 0.f;
.LBB0_56:
	s_waitcnt lgkmcnt(0)
	global_load_dwordx4 v[14:17], v[4:5], off offset:-3072
	global_load_dwordx4 v[22:25], v[4:5], off offset:-2048
	global_load_dwordx4 v[26:29], v[4:5], off offset:-1024
	global_load_dwordx4 v[30:33], v[4:5], off
	s_mov_b32 s6, 0x3a00000
	s_waitcnt vmcnt(0)
	v_mul_f32_e32 v13, v15, v15
	v_mul_f32_e32 v18, v17, v17
	v_mul_f32_e32 v19, v23, v23
	v_mul_f32_e32 v21, v25, v25
	v_mul_f32_e32 v34, v27, v27
	v_mul_f32_e32 v35, v29, v29
	v_fmac_f32_e32 v13, v14, v14
	v_fmac_f32_e32 v18, v16, v16
	v_fmac_f32_e32 v19, v22, v22
	v_fmac_f32_e32 v21, v24, v24
	v_mul_f32_e32 v36, v31, v31
	v_mul_f32_e32 v37, v33, v33
	v_fmac_f32_e32 v34, v26, v26
	v_fmac_f32_e32 v35, v28, v28
	v_add_f32_e32 v13, v13, v18
	v_add_f32_e32 v18, v19, v21
	v_fmac_f32_e32 v36, v30, v30
	v_fmac_f32_e32 v37, v32, v32
	v_add_f32_e32 v19, v34, v35
	v_add_f32_e32 v13, v13, v18
	v_add_f32_e32 v21, v36, v37
	v_add_f32_e32 v13, v13, v19
	v_add_f32_e32 v13, v13, v21
	s_nop 1
	v_mov_b32_dpp v18, v13 quad_perm:[1,0,3,2] row_mask:0xf bank_mask:0xf
	v_cvt_pk_bf16_f32 v14, v14, v15
	v_cvt_pk_bf16_f32 v15, v16, v17
	v_cvt_pk_bf16_f32 v16, v22, v23
	v_cvt_pk_bf16_f32 v17, v24, v25
	s_waitcnt lgkmcnt(0)
	v_add_f32_e32 v13, v13, v18
	s_nop 1
	v_mov_b32_dpp v18, v13 quad_perm:[2,3,0,1] row_mask:0xf bank_mask:0xf
	v_cvt_pk_bf16_f32 v22, v26, v27
	v_cvt_pk_bf16_f32 v23, v28, v29
	s_waitcnt lgkmcnt(0)
	v_add_f32_e32 v13, v13, v18
	s_nop 1
	v_mov_b32_dpp v21, v13 row_half_mirror row_mask:0xf bank_mask:0xf
	v_lshl_add_u64 v[18:19], s[10:11], 0, v[2:3]
	v_add_co_u32_e64 v18, s[6:7], s6, v18
	s_waitcnt lgkmcnt(0)
	v_add_f32_e32 v13, v13, v21
	s_nop 1
	v_mov_b32_dpp v21, v13 row_ror:8 row_mask:0xf bank_mask:0xf
	v_addc_co_u32_e64 v19, s[6:7], 0, v19, s[6:7]
	global_store_dwordx2 v[18:19], v[14:15], off
	global_store_dwordx2 v[18:19], v[16:17], off offset:512
	v_cvt_pk_bf16_f32 v16, v30, v31
	s_waitcnt lgkmcnt(0)
	v_add_f32_e32 v13, v13, v21
	v_mov_b32_e32 v21, v13
	s_nop 1
	v_permlane16_swap_b32_e32 v13, v21
	v_cvt_pk_bf16_f32 v17, v32, v33
	global_store_dwordx2 v[18:19], v[22:23], off offset:1024
	global_store_dwordx2 v[18:19], v[16:17], off offset:1536
	s_waitcnt lgkmcnt(0)
	v_add_f32_e32 v13, v13, v21
	v_mov_b32_e32 v14, v13
	s_nop 1
	v_permlane32_swap_b32_e32 v13, v14
	s_and_saveexec_b64 s[6:7], vcc
	s_cbranch_execz .LBB0_55
	s_waitcnt lgkmcnt(0)
	v_add_f32_e32 v13, v13, v14
	v_lshl_add_u64 v[16:17], s[10:11], 0, v[0:1]
	v_cndmask_b32_e64 v13, 0, v13, s[4:5]
	global_store_dword v[16:17], v13, off
	s_branch .LBB0_55
